# P2 u/bg tiles: full-line stores (w_in rows of column tiles 0,1,4,5 reordered in P0, DPP lane-pair exchange), on top of v-tile full-line stores
# baseline (speedup 1.0000x reference)
; __device__ __forceinline__ unsigned cvt_pk_bf16(float lo, float hi) { unsigned r; asm("v_cvt_pk_bf16_f32 %0, %1, %2" : "=v"(r) : "v"(lo), "v"(hi)); return r; }
; __device__ __forceinline__ int win_src_col(int np) {
;     const int tile = np >> 8, s = np & 255;
;     if (tile < 2 || tile == 4 || tile == 5) return np;
; template <bool PERMW, bool PERM32>
; __device__ __forceinline__ void transpose_cvt(const float* __restrict__ src, bf16_t* __restrict__ dst, int K, int N, float* T, int& tile_ctr, int blk, int nblk) {
;     ...
;         const int k0 = (tl % nkt) * 64, n0 = (tl / nkt) * 256;
;         { const int n4 = (tid & 63) * 4, sc = PERMW ? win_src_col(n0 + n4) : n0 + n4; f32x4 v[8];
; #pragma unroll
;           for (int i = 0; i < 8; ++i) { const int k = (tid >> 6) + 8 * i; v[i] = *(const f32x4*)(src + (size_t)(k0 + k) * N + sc); }
; #pragma unroll
;           for (int i = 0; i < 8; ++i) { const int k = (tid >> 6) + 8 * i; *(f32x4*)(T + k * 256 + (n4 ^ (((k >> 3) & 7) << 2))) = v[i]; } }
;         __syncthreads();
; #pragma unroll
;         for (int i = 0; i < 4; ++i) { const int pi = tid + 512 * i, q = pi & 7, nl = pi >> 3, x = PERM32 ? (nl & ~31) + perm32(nl & 31) : nl; const float* tp = T + (8 * q) * 256 + (x ^ (q << 2)); uint4 o;
;             o.x = cvt_pk_bf16(tp[0], tp[256]); o.y = cvt_pk_bf16(tp[512], tp[768]); o.z = cvt_pk_bf16(tp[1024], tp[1280]); o.w = cvt_pk_bf16(tp[1536], tp[1792]);
;             *(uint4*)(dst + (size_t)(n0 + nl) * K + k0 + 8 * q) = o; }
.LBB0_25:
	s_lshl_b32 s14, s73, 10
	s_sub_i32 s14, s70, s14
	v_add_u32_e32 v52, s14, v10
	v_ashrrev_i32_e32 v7, 31, v6
	v_lshl_add_u64 v[6:7], v[6:7], 2, s[16:17]
	v_add_u32_e32 v28, 8, v52
	v_add_u32_e32 v34, 16, v52
	v_add_u32_e32 v36, 24, v52
	v_add_u32_e32 v42, 32, v52
	v_add_u32_e32 v44, 40, v52
	v_add_u32_e32 v50, 48, v52
	v_mad_i64_i32 v[26:27], s[74:75], v52, s67, v[6:7]
	v_mad_i64_i32 v[30:31], s[74:75], v28, s67, v[6:7]
	v_mad_i64_i32 v[34:35], s[74:75], v34, s67, v[6:7]
	v_mad_i64_i32 v[38:39], s[74:75], v36, s67, v[6:7]
	v_mad_i64_i32 v[42:43], s[74:75], v42, s67, v[6:7]
	v_mad_i64_i32 v[46:47], s[74:75], v44, s67, v[6:7]
	v_mad_i64_i32 v[50:51], s[74:75], v50, s67, v[6:7]
	v_add_u32_e32 v52, 56, v52
	global_load_dwordx4 v[26:29], v[26:27], off nt
	s_nop 0
	global_load_dwordx4 v[30:33], v[30:31], off nt
	s_nop 0
	global_load_dwordx4 v[34:37], v[34:35], off nt
	s_nop 0
	global_load_dwordx4 v[38:41], v[38:39], off nt
	s_nop 0
	global_load_dwordx4 v[42:45], v[42:43], off nt
	s_nop 0
	global_load_dwordx4 v[46:49], v[46:47], off nt
	v_mad_i64_i32 v[6:7], s[74:75], v52, s67, v[6:7]
	global_load_dwordx4 v[50:53], v[50:51], off nt
	s_nop 0
	global_load_dwordx4 v[54:57], v[6:7], off nt
	v_lshrrev_b32_e32 v58, 5, v2
	v_mad_u32_u24 v6, v58, s76, v2
	v_add_u32_e32 v6, s72, v6
	v_add_u32_e32 v58, s77, v6
	v_lshl_add_u32 v60, s77, 1, v6
	v_ashrrev_i32_e32 v7, 31, v6
	s_ashr_i32 s15, s14, 31
	v_ashrrev_i32_e32 v59, 31, v58
	v_ashrrev_i32_e32 v61, 31, v60
	v_lshlrev_b64 v[6:7], 11, v[6:7]
	v_lshl_add_u64 v[62:63], s[14:15], 1, v[4:5]
	v_lshlrev_b64 v[58:59], 11, v[58:59]
	v_lshlrev_b64 v[60:61], 11, v[60:61]
	v_lshl_add_u64 v[6:7], v[62:63], 0, v[6:7]
	v_lshl_add_u64 v[58:59], v[62:63], 0, v[58:59]
	v_lshl_add_u64 v[60:61], v[62:63], 0, v[60:61]
	s_add_i32 s69, s69, s33
	s_add_i32 s70, s70, s71
	s_cmpk_lt_i32 s69, 0xa0
	s_waitcnt vmcnt(7)
	ds_write_b128 v12, v[26:29]
	s_waitcnt vmcnt(6)
	ds_write_b128 v13, v[30:33]
	s_waitcnt vmcnt(5)
	ds_write_b128 v14, v[34:37]
	s_waitcnt vmcnt(4)
	ds_write_b128 v15, v[38:41]
	s_waitcnt vmcnt(3)
	ds_write_b128 v16, v[42:45]
	s_waitcnt vmcnt(2)
	ds_write_b128 v17, v[46:49]
	s_waitcnt vmcnt(1)
	ds_write_b128 v18, v[50:53]
	s_waitcnt vmcnt(0)
	ds_write_b128 v19, v[54:57]
	s_waitcnt lgkmcnt(0)
	s_barrier
	ds_read2st64_b32 v[26:27], v11 offset1:4
	ds_read2st64_b32 v[28:29], v11 offset0:8 offset1:12
	ds_read2st64_b32 v[30:31], v11 offset0:16 offset1:20
	ds_read2st64_b32 v[32:33], v11 offset0:24 offset1:28
	ds_read2st64_b32 v[34:35], v21 offset1:4
	ds_read2st64_b32 v[36:37], v21 offset0:8 offset1:12
	ds_read2st64_b32 v[38:39], v21 offset0:16 offset1:20
	ds_read2st64_b32 v[40:41], v21 offset0:24 offset1:28
	ds_read2st64_b32 v[42:43], v23 offset1:4
	ds_read2st64_b32 v[44:45], v23 offset0:8 offset1:12
	ds_read2st64_b32 v[46:47], v23 offset0:16 offset1:20
	ds_read2st64_b32 v[48:49], v23 offset0:24 offset1:28
	ds_read2st64_b32 v[50:51], v25 offset1:4
	ds_read2st64_b32 v[52:53], v25 offset0:8 offset1:12
	ds_read2st64_b32 v[54:55], v25 offset0:16 offset1:20
	ds_read2st64_b32 v[56:57], v25 offset0:24 offset1:28
	s_waitcnt lgkmcnt(14)
	v_cvt_pk_bf16_f32 v26, v26, v27
	v_cvt_pk_bf16_f32 v27, v28, v29
	s_waitcnt lgkmcnt(13)
	v_cvt_pk_bf16_f32 v28, v30, v31
	s_waitcnt lgkmcnt(12)
	v_cvt_pk_bf16_f32 v29, v32, v33
	s_waitcnt lgkmcnt(11)
	v_cvt_pk_bf16_f32 v30, v34, v35
	s_waitcnt lgkmcnt(10)
	v_cvt_pk_bf16_f32 v31, v36, v37
	s_waitcnt lgkmcnt(9)
	v_cvt_pk_bf16_f32 v32, v38, v39
	s_waitcnt lgkmcnt(8)
	v_cvt_pk_bf16_f32 v33, v40, v41
	s_waitcnt lgkmcnt(7)
	v_cvt_pk_bf16_f32 v34, v42, v43
	s_waitcnt lgkmcnt(6)
	v_cvt_pk_bf16_f32 v35, v44, v45
	s_waitcnt lgkmcnt(5)
	v_cvt_pk_bf16_f32 v36, v46, v47
	s_waitcnt lgkmcnt(4)
	v_cvt_pk_bf16_f32 v37, v48, v49
	global_store_dwordx4 v[6:7], v[26:29], off
	global_store_dwordx4 v[58:59], v[30:33], off
	global_store_dwordx4 v[60:61], v[34:37], off
	v_lshrrev_b32_e32 v6, 5, v2
	v_mad_u32_u24 v6, v6, s76, v2
	v_add_u32_e32 v6, s72, v6
	s_mul_i32 s78, s77, 3
	v_add_u32_e32 v6, s78, v6
	v_ashrrev_i32_e32 v7, 31, v6
	v_lshlrev_b64 v[6:7], 11, v[6:7]
	v_lshl_add_u64 v[6:7], v[62:63], 0, v[6:7]
	s_waitcnt lgkmcnt(3)
	v_cvt_pk_bf16_f32 v26, v50, v51
	s_waitcnt lgkmcnt(2)
	v_cvt_pk_bf16_f32 v27, v52, v53
	s_waitcnt lgkmcnt(1)
	v_cvt_pk_bf16_f32 v28, v54, v55
	s_waitcnt lgkmcnt(0)
	v_cvt_pk_bf16_f32 v29, v56, v57
	global_store_dwordx4 v[6:7], v[26:29], off
	s_barrier
	s_cbranch_scc0 .LBB0_31
.LBB0_26:
	s_ashr_i32 s14, s69, 31
	s_lshr_b32 s14, s14, 28
	s_add_i32 s14, s69, s14
	s_ashr_i32 s73, s14, 4
	s_lshl_b32 s72, s73, 8
	s_cmp_lt_i32 s69, 32
	s_cselect_b64 s[14:15], -1, 0
	s_and_b32 s74, s73, 0xfffffe
	s_cmp_eq_u32 s74, 4
	s_cselect_b64 s[74:75], -1, 0
	s_or_b64 s[14:15], s[14:15], s[74:75]
	s_cselect_b32 s76, 0x60, 0
	s_cselect_b32 s77, 32, 64
	v_or_b32_e32 v6, s72, v1
	s_and_b64 vcc, exec, s[14:15]
	s_cbranch_vccnz .LBB0_25
	s_cmp_gt_u32 s73, 3
	s_mov_b64 s[14:15], -1
	s_cbranch_scc0 .LBB0_29
	v_lshlrev_b32_e32 v7, 2, v6
	v_and_b32_e32 v7, 0x200, v7
	s_lshl_b32 s14, s73, 7
	v_add3_u32 v7, v8, s14, v7
	s_mov_b64 s[14:15], 0

; __device__ __forceinline__ float gelu_tanh(float x) { const float u = 1.5957691216f * (x + 0.044715f * x * x * x); return x * __builtin_amdgcn_rcpf(1.f + __expf(-u)); }
; __device__ __forceinline__ void st_bf16x8(bf16_t* p, const f32x4 a, const f32x4 b) { uint4 o; o.x = cvt_pk_bf16(a[0], a[1]); o.y = cvt_pk_bf16(a[2], a[3]); o.z = cvt_pk_bf16(b[0], b[1]); o.w = cvt_pk_bf16(b[2], b[3]); *(uint4*)p = o; }
;     __device__ __forceinline__ void row(const f32x4 (&a)[2][2], int row, int pn, int wc, int fq) const {
;         if (pn < 2 || pn == 4 || pn == 5) {
;             bf16_t* dst = (pn < 2 ? pU : pBG) + (size_t)row * 512 + (pn & 1) * 256 + wc * 32 + 8 * fq;
; #pragma unroll
;             for (int bj = 0; bj < 2; ++bj) { f32x4 v0 = a[bj][0], v1 = a[bj][1];
;                 if (pn < 2) {
; #pragma unroll
;                     for (int j = 0; j < 4; ++j) { v0[j] = gelu_tanh(v0[j]); v1[j] = gelu_tanh(v1[j]); } }
;                 st_bf16x8(dst + bj * HALF, v0, v1); }
.LBB0_207:
	v_cvt_pk_bf16_f32 v4, v4, v5
	v_cvt_pk_bf16_f32 v5, v6, v7
	v_cvt_pk_bf16_f32 v6, v0, v1
	v_cvt_pk_bf16_f32 v7, v2, v3
	s_mov_b64 s[100:101], vcc
	v_and_b32_e32 v222, 1, v24
	s_movk_i32 s32, 0xfc40
	v_mad_i64_i32 v[16:17], s[98:99], v222, s32, v[16:17]
	v_cmp_eq_u32_e32 vcc, 0, v222
	s_nop 1
	v_cndmask_b32_dpp v208, v4, v204, vcc quad_perm:[1,0,3,2] row_mask:0xf bank_mask:0xf
	v_cndmask_b32_dpp v209, v5, v205, vcc quad_perm:[1,0,3,2] row_mask:0xf bank_mask:0xf
	v_cndmask_b32_dpp v210, v6, v206, vcc quad_perm:[1,0,3,2] row_mask:0xf bank_mask:0xf
	v_cndmask_b32_dpp v211, v7, v207, vcc quad_perm:[1,0,3,2] row_mask:0xf bank_mask:0xf
	v_cmp_ne_u32_e32 vcc, 0, v222
	s_nop 1
	v_cndmask_b32_dpp v4, v204, v4, vcc quad_perm:[1,0,3,2] row_mask:0xf bank_mask:0xf
	v_cndmask_b32_dpp v5, v205, v5, vcc quad_perm:[1,0,3,2] row_mask:0xf bank_mask:0xf
	v_cndmask_b32_dpp v6, v206, v6, vcc quad_perm:[1,0,3,2] row_mask:0xf bank_mask:0xf
	v_cndmask_b32_dpp v7, v207, v7, vcc quad_perm:[1,0,3,2] row_mask:0xf bank_mask:0xf
	global_store_dwordx4 v[16:17], v[208:211], off
	global_store_dwordx4 v[16:17], v[4:7], off offset:1024
	s_mov_b64 vcc, s[100:101]

; __device__ __forceinline__ float gelu_tanh(float x) { const float u = 1.5957691216f * (x + 0.044715f * x * x * x); return x * __builtin_amdgcn_rcpf(1.f + __expf(-u)); }
; __device__ __forceinline__ void st_bf16x8(bf16_t* p, const f32x4 a, const f32x4 b) { uint4 o; o.x = cvt_pk_bf16(a[0], a[1]); o.y = cvt_pk_bf16(a[2], a[3]); o.z = cvt_pk_bf16(b[0], b[1]); o.w = cvt_pk_bf16(b[2], b[3]); *(uint4*)p = o; }
;     __device__ __forceinline__ void row(const f32x4 (&a)[2][2], int row, int pn, int wc, int fq) const {
;         if (pn < 2 || pn == 4 || pn == 5) {
;             bf16_t* dst = (pn < 2 ? pU : pBG) + (size_t)row * 512 + (pn & 1) * 256 + wc * 32 + 8 * fq;
; #pragma unroll
;             for (int bj = 0; bj < 2; ++bj) { f32x4 v0 = a[bj][0], v1 = a[bj][1];
;                 if (pn < 2) {
; #pragma unroll
;                     for (int j = 0; j < 4; ++j) { v0[j] = gelu_tanh(v0[j]); v1[j] = gelu_tanh(v1[j]); } }
;                 st_bf16x8(dst + bj * HALF, v0, v1); }
.LBB0_227:
	s_and_b64 s[0:1], s[80:81], exec
	v_ashrrev_i32_e32 v157, 31, v156
	s_cselect_b32 s1, s31, s49
	s_cselect_b32 s0, s30, s48
	v_lshlrev_b64 v[128:129], 10, v[156:157]
	v_lshl_add_u64 v[128:129], s[0:1], 0, v[128:129]
	s_lshl_b32 s64, s61, 1
	v_lshl_add_u64 v[128:129], v[128:129], 0, s[64:65]
	s_lshl_b32 s64, s91, 2
	v_lshl_add_u64 v[128:129], v[128:129], 0, s[64:65]
	v_lshlrev_b32_e32 v130, 1, v142
	v_mov_b32_e32 v131, v141
	v_lshl_add_u64 v[128:129], v[128:129], 0, v[130:131]
	s_and_b64 vcc, exec, s[4:5]
	v_cvt_pk_bf16_f32 v124, v124, v125
	v_cvt_pk_bf16_f32 v125, v126, v127
	v_cvt_pk_bf16_f32 v126, v120, v121
	v_cvt_pk_bf16_f32 v127, v122, v123
	v_mov_b64_e32 v[204:205], v[124:125]
	v_mov_b64_e32 v[206:207], v[126:127]
	s_cbranch_vccnz .LBB0_229
	v_mov_b32_e32 v190, 0x3d372713
	v_mov_b32_e32 v192, 0xbfcc422a
	v_mov_b32_e32 v194, 0x3fb8aa3b
	v_pk_mul_f32 v[196:197], v[112:113], v[190:191] op_sel_hi:[1,0]
	v_pk_mul_f32 v[198:199], v[114:115], v[190:191] op_sel_hi:[1,0]
	v_pk_mul_f32 v[200:201], v[116:117], v[190:191] op_sel_hi:[1,0]
	v_pk_mul_f32 v[202:203], v[118:119], v[190:191] op_sel_hi:[1,0]
	v_pk_mul_f32 v[196:197], v[112:113], v[196:197]
	v_pk_mul_f32 v[198:199], v[114:115], v[198:199]
	v_pk_mul_f32 v[200:201], v[116:117], v[200:201]
	v_pk_mul_f32 v[202:203], v[118:119], v[202:203]
	v_pk_fma_f32 v[196:197], v[112:113], v[196:197], v[112:113]
	v_pk_fma_f32 v[198:199], v[114:115], v[198:199], v[114:115]
	v_pk_fma_f32 v[200:201], v[116:117], v[200:201], v[116:117]
	v_pk_fma_f32 v[202:203], v[118:119], v[202:203], v[118:119]
	v_pk_mul_f32 v[196:197], v[196:197], v[192:193] op_sel_hi:[1,0]
	v_pk_mul_f32 v[198:199], v[198:199], v[192:193] op_sel_hi:[1,0]
	v_pk_mul_f32 v[200:201], v[200:201], v[192:193] op_sel_hi:[1,0]
	v_pk_mul_f32 v[202:203], v[202:203], v[192:193] op_sel_hi:[1,0]
	v_pk_mul_f32 v[196:197], v[196:197], v[194:195] op_sel_hi:[1,0]
	v_pk_mul_f32 v[198:199], v[198:199], v[194:195] op_sel_hi:[1,0]
	v_pk_mul_f32 v[200:201], v[200:201], v[194:195] op_sel_hi:[1,0]
	v_pk_mul_f32 v[202:203], v[202:203], v[194:195] op_sel_hi:[1,0]
	v_exp_f32_e32 v196, v196
	v_exp_f32_e32 v197, v197
	v_exp_f32_e32 v198, v198
	v_exp_f32_e32 v199, v199
	v_exp_f32_e32 v200, v200
	v_exp_f32_e32 v201, v201
	v_exp_f32_e32 v202, v202
	v_exp_f32_e32 v203, v203
	v_pk_add_f32 v[196:197], v[196:197], 1.0 op_sel_hi:[1,0]
	v_pk_add_f32 v[198:199], v[198:199], 1.0 op_sel_hi:[1,0]
	v_pk_add_f32 v[200:201], v[200:201], 1.0 op_sel_hi:[1,0]
	v_pk_add_f32 v[202:203], v[202:203], 1.0 op_sel_hi:[1,0]
	v_rcp_f32_e32 v196, v196
	v_rcp_f32_e32 v197, v197
	v_rcp_f32_e32 v198, v198
	v_rcp_f32_e32 v199, v199
	v_rcp_f32_e32 v200, v200
	v_rcp_f32_e32 v201, v201
	v_rcp_f32_e32 v202, v202
	v_rcp_f32_e32 v203, v203
	v_pk_mul_f32 v[112:113], v[112:113], v[196:197]
	v_pk_mul_f32 v[114:115], v[114:115], v[198:199]
	v_pk_mul_f32 v[116:117], v[116:117], v[200:201]
	v_pk_mul_f32 v[118:119], v[118:119], v[202:203]
	s_nop 0
	s_nop 0
	s_nop 0
	s_nop 0
.LBB0_229:
	v_cvt_pk_bf16_f32 v116, v116, v117
	v_cvt_pk_bf16_f32 v117, v118, v119
	v_cvt_pk_bf16_f32 v118, v112, v113
	s_nop 0
	v_cvt_pk_bf16_f32 v119, v114, v115
	s_mov_b64 s[100:101], vcc
	v_and_b32_e32 v222, 1, v156
	s_movk_i32 s32, 0xfc40
	v_mad_i64_i32 v[128:129], s[98:99], v222, s32, v[128:129]
	v_cmp_eq_u32_e32 vcc, 0, v222
	s_nop 1
	v_cndmask_b32_dpp v208, v116, v204, vcc quad_perm:[1,0,3,2] row_mask:0xf bank_mask:0xf
	v_cndmask_b32_dpp v209, v117, v205, vcc quad_perm:[1,0,3,2] row_mask:0xf bank_mask:0xf
	v_cndmask_b32_dpp v210, v118, v206, vcc quad_perm:[1,0,3,2] row_mask:0xf bank_mask:0xf
	v_cndmask_b32_dpp v211, v119, v207, vcc quad_perm:[1,0,3,2] row_mask:0xf bank_mask:0xf
	v_cmp_ne_u32_e32 vcc, 0, v222
	s_nop 1
	v_cndmask_b32_dpp v116, v204, v116, vcc quad_perm:[1,0,3,2] row_mask:0xf bank_mask:0xf
	v_cndmask_b32_dpp v117, v205, v117, vcc quad_perm:[1,0,3,2] row_mask:0xf bank_mask:0xf
	v_cndmask_b32_dpp v118, v206, v118, vcc quad_perm:[1,0,3,2] row_mask:0xf bank_mask:0xf
	v_cndmask_b32_dpp v119, v207, v119, vcc quad_perm:[1,0,3,2] row_mask:0xf bank_mask:0xf
	global_store_dwordx4 v[128:129], v[208:211], off
	global_store_dwordx4 v[128:129], v[116:119], off offset:1024
	s_mov_b64 vcc, s[100:101]

; __device__ __forceinline__ float gelu_tanh(float x) { const float u = 1.5957691216f * (x + 0.044715f * x * x * x); return x * __builtin_amdgcn_rcpf(1.f + __expf(-u)); }
; __device__ __forceinline__ void st_bf16x8(bf16_t* p, const f32x4 a, const f32x4 b) { uint4 o; o.x = cvt_pk_bf16(a[0], a[1]); o.y = cvt_pk_bf16(a[2], a[3]); o.z = cvt_pk_bf16(b[0], b[1]); o.w = cvt_pk_bf16(b[2], b[3]); *(uint4*)p = o; }
;     __device__ __forceinline__ void row(const f32x4 (&a)[2][2], int row, int pn, int wc, int fq) const {
;         if (pn < 2 || pn == 4 || pn == 5) {
;             bf16_t* dst = (pn < 2 ? pU : pBG) + (size_t)row * 512 + (pn & 1) * 256 + wc * 32 + 8 * fq;
; #pragma unroll
;             for (int bj = 0; bj < 2; ++bj) { f32x4 v0 = a[bj][0], v1 = a[bj][1];
;                 if (pn < 2) {
; #pragma unroll
;                     for (int j = 0; j < 4; ++j) { v0[j] = gelu_tanh(v0[j]); v1[j] = gelu_tanh(v1[j]); } }
;                 st_bf16x8(dst + bj * HALF, v0, v1); }
.LBB0_248:
	s_and_b64 s[0:1], s[80:81], exec
	v_ashrrev_i32_e32 v121, 31, v120
	s_cselect_b32 s1, s31, s49
	s_cselect_b32 s0, s30, s48
	v_lshlrev_b64 v[112:113], 10, v[120:121]
	v_lshl_add_u64 v[112:113], s[0:1], 0, v[112:113]
	s_lshl_b32 s64, s61, 1
	v_lshl_add_u64 v[112:113], v[112:113], 0, s[64:65]
	s_lshl_b32 s64, s91, 2
	v_lshl_add_u64 v[112:113], v[112:113], 0, s[64:65]
	v_lshlrev_b32_e32 v114, 1, v142
	v_mov_b32_e32 v115, v141
	v_lshl_add_u64 v[112:113], v[112:113], 0, v[114:115]
	s_and_b64 vcc, exec, s[4:5]
	v_cvt_pk_bf16_f32 v108, v108, v109
	v_cvt_pk_bf16_f32 v109, v110, v111
	v_cvt_pk_bf16_f32 v110, v104, v105
	v_cvt_pk_bf16_f32 v111, v106, v107
	v_mov_b64_e32 v[204:205], v[108:109]
	v_mov_b64_e32 v[206:207], v[110:111]
	s_cbranch_vccnz .LBB0_250
	v_mov_b32_e32 v190, 0x3d372713
	v_mov_b32_e32 v192, 0xbfcc422a
	v_mov_b32_e32 v194, 0x3fb8aa3b
	v_pk_mul_f32 v[196:197], v[96:97], v[190:191] op_sel_hi:[1,0]
	v_pk_mul_f32 v[198:199], v[98:99], v[190:191] op_sel_hi:[1,0]
	v_pk_mul_f32 v[200:201], v[100:101], v[190:191] op_sel_hi:[1,0]
	v_pk_mul_f32 v[202:203], v[102:103], v[190:191] op_sel_hi:[1,0]
	v_pk_mul_f32 v[196:197], v[96:97], v[196:197]
	v_pk_mul_f32 v[198:199], v[98:99], v[198:199]
	v_pk_mul_f32 v[200:201], v[100:101], v[200:201]
	v_pk_mul_f32 v[202:203], v[102:103], v[202:203]
	v_pk_fma_f32 v[196:197], v[96:97], v[196:197], v[96:97]
	v_pk_fma_f32 v[198:199], v[98:99], v[198:199], v[98:99]
	v_pk_fma_f32 v[200:201], v[100:101], v[200:201], v[100:101]
	v_pk_fma_f32 v[202:203], v[102:103], v[202:203], v[102:103]
	v_pk_mul_f32 v[196:197], v[196:197], v[192:193] op_sel_hi:[1,0]
	v_pk_mul_f32 v[198:199], v[198:199], v[192:193] op_sel_hi:[1,0]
	v_pk_mul_f32 v[200:201], v[200:201], v[192:193] op_sel_hi:[1,0]
	v_pk_mul_f32 v[202:203], v[202:203], v[192:193] op_sel_hi:[1,0]
	v_pk_mul_f32 v[196:197], v[196:197], v[194:195] op_sel_hi:[1,0]
	v_pk_mul_f32 v[198:199], v[198:199], v[194:195] op_sel_hi:[1,0]
	v_pk_mul_f32 v[200:201], v[200:201], v[194:195] op_sel_hi:[1,0]
	v_pk_mul_f32 v[202:203], v[202:203], v[194:195] op_sel_hi:[1,0]
	v_exp_f32_e32 v196, v196
	v_exp_f32_e32 v197, v197
	v_exp_f32_e32 v198, v198
	v_exp_f32_e32 v199, v199
	v_exp_f32_e32 v200, v200
	v_exp_f32_e32 v201, v201
	v_exp_f32_e32 v202, v202
	v_exp_f32_e32 v203, v203
	v_pk_add_f32 v[196:197], v[196:197], 1.0 op_sel_hi:[1,0]
	v_pk_add_f32 v[198:199], v[198:199], 1.0 op_sel_hi:[1,0]
	v_pk_add_f32 v[200:201], v[200:201], 1.0 op_sel_hi:[1,0]
	v_pk_add_f32 v[202:203], v[202:203], 1.0 op_sel_hi:[1,0]
	v_rcp_f32_e32 v196, v196
	v_rcp_f32_e32 v197, v197
	v_rcp_f32_e32 v198, v198
	v_rcp_f32_e32 v199, v199
	v_rcp_f32_e32 v200, v200
	v_rcp_f32_e32 v201, v201
	v_rcp_f32_e32 v202, v202
	v_rcp_f32_e32 v203, v203
	v_pk_mul_f32 v[96:97], v[96:97], v[196:197]
	v_pk_mul_f32 v[98:99], v[98:99], v[198:199]
	v_pk_mul_f32 v[100:101], v[100:101], v[200:201]
	v_pk_mul_f32 v[102:103], v[102:103], v[202:203]
	s_nop 0
	s_nop 0
	s_nop 0
	s_nop 0
.LBB0_250:
	v_cvt_pk_bf16_f32 v100, v100, v101
	v_cvt_pk_bf16_f32 v101, v102, v103
	v_cvt_pk_bf16_f32 v102, v96, v97
	s_nop 0
	v_cvt_pk_bf16_f32 v103, v98, v99
	s_mov_b64 s[100:101], vcc
	v_and_b32_e32 v222, 1, v120
	s_movk_i32 s32, 0xfc40
	v_mad_i64_i32 v[112:113], s[98:99], v222, s32, v[112:113]
	v_cmp_eq_u32_e32 vcc, 0, v222
	s_nop 1
	v_cndmask_b32_dpp v208, v100, v204, vcc quad_perm:[1,0,3,2] row_mask:0xf bank_mask:0xf
	v_cndmask_b32_dpp v209, v101, v205, vcc quad_perm:[1,0,3,2] row_mask:0xf bank_mask:0xf
	v_cndmask_b32_dpp v210, v102, v206, vcc quad_perm:[1,0,3,2] row_mask:0xf bank_mask:0xf
	v_cndmask_b32_dpp v211, v103, v207, vcc quad_perm:[1,0,3,2] row_mask:0xf bank_mask:0xf
	v_cmp_ne_u32_e32 vcc, 0, v222
	s_nop 1
	v_cndmask_b32_dpp v100, v204, v100, vcc quad_perm:[1,0,3,2] row_mask:0xf bank_mask:0xf
	v_cndmask_b32_dpp v101, v205, v101, vcc quad_perm:[1,0,3,2] row_mask:0xf bank_mask:0xf
	v_cndmask_b32_dpp v102, v206, v102, vcc quad_perm:[1,0,3,2] row_mask:0xf bank_mask:0xf
	v_cndmask_b32_dpp v103, v207, v103, vcc quad_perm:[1,0,3,2] row_mask:0xf bank_mask:0xf
	global_store_dwordx4 v[112:113], v[208:211], off
	global_store_dwordx4 v[112:113], v[100:103], off offset:1024
	s_mov_b64 vcc, s[100:101]
	v_or_b32_e32 v104, 32, v156
	s_and_b64 vcc, exec, s[8:9]
	s_mov_b64 s[0:1], -1
	s_cbranch_vccnz .LBB0_233

; __device__ __forceinline__ float gelu_tanh(float x) { const float u = 1.5957691216f * (x + 0.044715f * x * x * x); return x * __builtin_amdgcn_rcpf(1.f + __expf(-u)); }
; __device__ __forceinline__ void st_bf16x8(bf16_t* p, const f32x4 a, const f32x4 b) { uint4 o; o.x = cvt_pk_bf16(a[0], a[1]); o.y = cvt_pk_bf16(a[2], a[3]); o.z = cvt_pk_bf16(b[0], b[1]); o.w = cvt_pk_bf16(b[2], b[3]); *(uint4*)p = o; }
;     __device__ __forceinline__ void row(const f32x4 (&a)[2][2], int row, int pn, int wc, int fq) const {
;         if (pn < 2 || pn == 4 || pn == 5) {
;             bf16_t* dst = (pn < 2 ? pU : pBG) + (size_t)row * 512 + (pn & 1) * 256 + wc * 32 + 8 * fq;
; #pragma unroll
;             for (int bj = 0; bj < 2; ++bj) { f32x4 v0 = a[bj][0], v1 = a[bj][1];
;                 if (pn < 2) {
; #pragma unroll
;                     for (int j = 0; j < 4; ++j) { v0[j] = gelu_tanh(v0[j]); v1[j] = gelu_tanh(v1[j]); } }
;                 st_bf16x8(dst + bj * HALF, v0, v1); }
.LBB0_263:
	s_and_b64 s[0:1], s[80:81], exec
	v_ashrrev_i32_e32 v105, 31, v104
	s_cselect_b32 s1, s31, s49
	s_cselect_b32 s0, s30, s48
	v_lshlrev_b64 v[96:97], 10, v[104:105]
	v_lshl_add_u64 v[96:97], s[0:1], 0, v[96:97]
	s_lshl_b32 s64, s61, 1
	v_lshl_add_u64 v[96:97], v[96:97], 0, s[64:65]
	s_lshl_b32 s64, s91, 2
	v_lshl_add_u64 v[96:97], v[96:97], 0, s[64:65]
	v_lshlrev_b32_e32 v98, 1, v142
	v_mov_b32_e32 v99, v141
	v_lshl_add_u64 v[96:97], v[96:97], 0, v[98:99]
	s_and_b64 vcc, exec, s[4:5]
	v_cvt_pk_bf16_f32 v92, v92, v93
	v_cvt_pk_bf16_f32 v93, v94, v95
	v_cvt_pk_bf16_f32 v94, v88, v89
	v_cvt_pk_bf16_f32 v95, v90, v91
	v_mov_b64_e32 v[204:205], v[92:93]
	v_mov_b64_e32 v[206:207], v[94:95]
	s_cbranch_vccnz .LBB0_265
	v_mov_b32_e32 v190, 0x3d372713
	v_mov_b32_e32 v192, 0xbfcc422a
	v_mov_b32_e32 v194, 0x3fb8aa3b
	v_pk_mul_f32 v[196:197], v[80:81], v[190:191] op_sel_hi:[1,0]
	v_pk_mul_f32 v[198:199], v[82:83], v[190:191] op_sel_hi:[1,0]
	v_pk_mul_f32 v[200:201], v[84:85], v[190:191] op_sel_hi:[1,0]
	v_pk_mul_f32 v[202:203], v[86:87], v[190:191] op_sel_hi:[1,0]
	v_pk_mul_f32 v[196:197], v[80:81], v[196:197]
	v_pk_mul_f32 v[198:199], v[82:83], v[198:199]
	v_pk_mul_f32 v[200:201], v[84:85], v[200:201]
	v_pk_mul_f32 v[202:203], v[86:87], v[202:203]
	v_pk_fma_f32 v[196:197], v[80:81], v[196:197], v[80:81]
	v_pk_fma_f32 v[198:199], v[82:83], v[198:199], v[82:83]
	v_pk_fma_f32 v[200:201], v[84:85], v[200:201], v[84:85]
	v_pk_fma_f32 v[202:203], v[86:87], v[202:203], v[86:87]
	v_pk_mul_f32 v[196:197], v[196:197], v[192:193] op_sel_hi:[1,0]
	v_pk_mul_f32 v[198:199], v[198:199], v[192:193] op_sel_hi:[1,0]
	v_pk_mul_f32 v[200:201], v[200:201], v[192:193] op_sel_hi:[1,0]
	v_pk_mul_f32 v[202:203], v[202:203], v[192:193] op_sel_hi:[1,0]
	v_pk_mul_f32 v[196:197], v[196:197], v[194:195] op_sel_hi:[1,0]
	v_pk_mul_f32 v[198:199], v[198:199], v[194:195] op_sel_hi:[1,0]
	v_pk_mul_f32 v[200:201], v[200:201], v[194:195] op_sel_hi:[1,0]
	v_pk_mul_f32 v[202:203], v[202:203], v[194:195] op_sel_hi:[1,0]
	v_exp_f32_e32 v196, v196
	v_exp_f32_e32 v197, v197
	v_exp_f32_e32 v198, v198
	v_exp_f32_e32 v199, v199
	v_exp_f32_e32 v200, v200
	v_exp_f32_e32 v201, v201
	v_exp_f32_e32 v202, v202
	v_exp_f32_e32 v203, v203
	v_pk_add_f32 v[196:197], v[196:197], 1.0 op_sel_hi:[1,0]
	v_pk_add_f32 v[198:199], v[198:199], 1.0 op_sel_hi:[1,0]
	v_pk_add_f32 v[200:201], v[200:201], 1.0 op_sel_hi:[1,0]
	v_pk_add_f32 v[202:203], v[202:203], 1.0 op_sel_hi:[1,0]
	v_rcp_f32_e32 v196, v196
	v_rcp_f32_e32 v197, v197
	v_rcp_f32_e32 v198, v198
	v_rcp_f32_e32 v199, v199
	v_rcp_f32_e32 v200, v200
	v_rcp_f32_e32 v201, v201
	v_rcp_f32_e32 v202, v202
	v_rcp_f32_e32 v203, v203
	v_pk_mul_f32 v[80:81], v[80:81], v[196:197]
	v_pk_mul_f32 v[82:83], v[82:83], v[198:199]
	v_pk_mul_f32 v[84:85], v[84:85], v[200:201]
	v_pk_mul_f32 v[86:87], v[86:87], v[202:203]
	s_nop 0
	s_nop 0
	s_nop 0
	s_nop 0
.LBB0_265:
	v_cvt_pk_bf16_f32 v84, v84, v85
	v_cvt_pk_bf16_f32 v85, v86, v87
	v_cvt_pk_bf16_f32 v86, v80, v81
	s_nop 0
	v_cvt_pk_bf16_f32 v87, v82, v83
	s_mov_b64 s[100:101], vcc
	v_and_b32_e32 v222, 1, v104
	s_movk_i32 s32, 0xfc40
	v_mad_i64_i32 v[96:97], s[98:99], v222, s32, v[96:97]
	v_cmp_eq_u32_e32 vcc, 0, v222
	s_nop 1
	v_cndmask_b32_dpp v208, v84, v204, vcc quad_perm:[1,0,3,2] row_mask:0xf bank_mask:0xf
	v_cndmask_b32_dpp v209, v85, v205, vcc quad_perm:[1,0,3,2] row_mask:0xf bank_mask:0xf
	v_cndmask_b32_dpp v210, v86, v206, vcc quad_perm:[1,0,3,2] row_mask:0xf bank_mask:0xf
	v_cndmask_b32_dpp v211, v87, v207, vcc quad_perm:[1,0,3,2] row_mask:0xf bank_mask:0xf
	v_cmp_ne_u32_e32 vcc, 0, v222
	s_nop 1
	v_cndmask_b32_dpp v84, v204, v84, vcc quad_perm:[1,0,3,2] row_mask:0xf bank_mask:0xf
	v_cndmask_b32_dpp v85, v205, v85, vcc quad_perm:[1,0,3,2] row_mask:0xf bank_mask:0xf
	v_cndmask_b32_dpp v86, v206, v86, vcc quad_perm:[1,0,3,2] row_mask:0xf bank_mask:0xf
	v_cndmask_b32_dpp v87, v207, v87, vcc quad_perm:[1,0,3,2] row_mask:0xf bank_mask:0xf
	global_store_dwordx4 v[96:97], v[208:211], off
	global_store_dwordx4 v[96:97], v[84:87], off offset:1024
	s_mov_b64 vcc, s[100:101]
	v_or_b32_e32 v88, 48, v156
	s_and_b64 vcc, exec, s[8:9]
	s_mov_b64 s[0:1], -1
	s_cbranch_vccnz .LBB0_235

; __device__ __forceinline__ float gelu_tanh(float x) { const float u = 1.5957691216f * (x + 0.044715f * x * x * x); return x * __builtin_amdgcn_rcpf(1.f + __expf(-u)); }
; __device__ __forceinline__ void st_bf16x8(bf16_t* p, const f32x4 a, const f32x4 b) { uint4 o; o.x = cvt_pk_bf16(a[0], a[1]); o.y = cvt_pk_bf16(a[2], a[3]); o.z = cvt_pk_bf16(b[0], b[1]); o.w = cvt_pk_bf16(b[2], b[3]); *(uint4*)p = o; }
;     __device__ __forceinline__ void row(const f32x4 (&a)[2][2], int row, int pn, int wc, int fq) const {
;         if (pn < 2 || pn == 4 || pn == 5) {
;             bf16_t* dst = (pn < 2 ? pU : pBG) + (size_t)row * 512 + (pn & 1) * 256 + wc * 32 + 8 * fq;
; #pragma unroll
;             for (int bj = 0; bj < 2; ++bj) { f32x4 v0 = a[bj][0], v1 = a[bj][1];
;                 if (pn < 2) {
; #pragma unroll
;                     for (int j = 0; j < 4; ++j) { v0[j] = gelu_tanh(v0[j]); v1[j] = gelu_tanh(v1[j]); } }
;                 st_bf16x8(dst + bj * HALF, v0, v1); }
.LBB0_280:
	s_and_b64 s[0:1], s[80:81], exec
	v_ashrrev_i32_e32 v89, 31, v88
	s_cselect_b32 s1, s31, s49
	s_cselect_b32 s0, s30, s48
	v_lshlrev_b64 v[80:81], 10, v[88:89]
	v_lshl_add_u64 v[80:81], s[0:1], 0, v[80:81]
	s_lshl_b32 s64, s61, 1
	v_lshl_add_u64 v[80:81], v[80:81], 0, s[64:65]
	s_lshl_b32 s64, s91, 2
	v_lshl_add_u64 v[80:81], v[80:81], 0, s[64:65]
	v_lshlrev_b32_e32 v82, 1, v142
	v_mov_b32_e32 v83, v141
	v_lshl_add_u64 v[80:81], v[80:81], 0, v[82:83]
	s_and_b64 vcc, exec, s[4:5]
	v_cvt_pk_bf16_f32 v76, v76, v77
	v_cvt_pk_bf16_f32 v77, v78, v79
	v_cvt_pk_bf16_f32 v78, v72, v73
	v_cvt_pk_bf16_f32 v79, v74, v75
	v_mov_b64_e32 v[204:205], v[76:77]
	v_mov_b64_e32 v[206:207], v[78:79]
	s_cbranch_vccnz .LBB0_282
	v_mov_b32_e32 v190, 0x3d372713
	v_mov_b32_e32 v192, 0xbfcc422a
	v_mov_b32_e32 v194, 0x3fb8aa3b
	v_pk_mul_f32 v[196:197], v[64:65], v[190:191] op_sel_hi:[1,0]
	v_pk_mul_f32 v[198:199], v[66:67], v[190:191] op_sel_hi:[1,0]
	v_pk_mul_f32 v[200:201], v[68:69], v[190:191] op_sel_hi:[1,0]
	v_pk_mul_f32 v[202:203], v[70:71], v[190:191] op_sel_hi:[1,0]
	v_pk_mul_f32 v[196:197], v[64:65], v[196:197]
	v_pk_mul_f32 v[198:199], v[66:67], v[198:199]
	v_pk_mul_f32 v[200:201], v[68:69], v[200:201]
	v_pk_mul_f32 v[202:203], v[70:71], v[202:203]
	v_pk_fma_f32 v[196:197], v[64:65], v[196:197], v[64:65]
	v_pk_fma_f32 v[198:199], v[66:67], v[198:199], v[66:67]
	v_pk_fma_f32 v[200:201], v[68:69], v[200:201], v[68:69]
	v_pk_fma_f32 v[202:203], v[70:71], v[202:203], v[70:71]
	v_pk_mul_f32 v[196:197], v[196:197], v[192:193] op_sel_hi:[1,0]
	v_pk_mul_f32 v[198:199], v[198:199], v[192:193] op_sel_hi:[1,0]
	v_pk_mul_f32 v[200:201], v[200:201], v[192:193] op_sel_hi:[1,0]
	v_pk_mul_f32 v[202:203], v[202:203], v[192:193] op_sel_hi:[1,0]
	v_pk_mul_f32 v[196:197], v[196:197], v[194:195] op_sel_hi:[1,0]
	v_pk_mul_f32 v[198:199], v[198:199], v[194:195] op_sel_hi:[1,0]
	v_pk_mul_f32 v[200:201], v[200:201], v[194:195] op_sel_hi:[1,0]
	v_pk_mul_f32 v[202:203], v[202:203], v[194:195] op_sel_hi:[1,0]
	v_exp_f32_e32 v196, v196
	v_exp_f32_e32 v197, v197
	v_exp_f32_e32 v198, v198
	v_exp_f32_e32 v199, v199
	v_exp_f32_e32 v200, v200
	v_exp_f32_e32 v201, v201
	v_exp_f32_e32 v202, v202
	v_exp_f32_e32 v203, v203
	v_pk_add_f32 v[196:197], v[196:197], 1.0 op_sel_hi:[1,0]
	v_pk_add_f32 v[198:199], v[198:199], 1.0 op_sel_hi:[1,0]
	v_pk_add_f32 v[200:201], v[200:201], 1.0 op_sel_hi:[1,0]
	v_pk_add_f32 v[202:203], v[202:203], 1.0 op_sel_hi:[1,0]
	v_rcp_f32_e32 v196, v196
	v_rcp_f32_e32 v197, v197
	v_rcp_f32_e32 v198, v198
	v_rcp_f32_e32 v199, v199
	v_rcp_f32_e32 v200, v200
	v_rcp_f32_e32 v201, v201
	v_rcp_f32_e32 v202, v202
	v_rcp_f32_e32 v203, v203
	v_pk_mul_f32 v[64:65], v[64:65], v[196:197]
	v_pk_mul_f32 v[66:67], v[66:67], v[198:199]
	v_pk_mul_f32 v[68:69], v[68:69], v[200:201]
	v_pk_mul_f32 v[70:71], v[70:71], v[202:203]
	s_nop 0
	s_nop 0
	s_nop 0
	s_nop 0
.LBB0_282:
	v_cvt_pk_bf16_f32 v68, v68, v69
	v_cvt_pk_bf16_f32 v69, v70, v71
	v_cvt_pk_bf16_f32 v70, v64, v65
	s_nop 0
	v_cvt_pk_bf16_f32 v71, v66, v67
	s_mov_b64 s[100:101], vcc
	v_and_b32_e32 v222, 1, v88
	s_movk_i32 s32, 0xfc40
	v_mad_i64_i32 v[80:81], s[98:99], v222, s32, v[80:81]
	v_cmp_eq_u32_e32 vcc, 0, v222
	s_nop 1
	v_cndmask_b32_dpp v208, v68, v204, vcc quad_perm:[1,0,3,2] row_mask:0xf bank_mask:0xf
	v_cndmask_b32_dpp v209, v69, v205, vcc quad_perm:[1,0,3,2] row_mask:0xf bank_mask:0xf
	v_cndmask_b32_dpp v210, v70, v206, vcc quad_perm:[1,0,3,2] row_mask:0xf bank_mask:0xf
	v_cndmask_b32_dpp v211, v71, v207, vcc quad_perm:[1,0,3,2] row_mask:0xf bank_mask:0xf
	v_cmp_ne_u32_e32 vcc, 0, v222
	s_nop 1
	v_cndmask_b32_dpp v68, v204, v68, vcc quad_perm:[1,0,3,2] row_mask:0xf bank_mask:0xf
	v_cndmask_b32_dpp v69, v205, v69, vcc quad_perm:[1,0,3,2] row_mask:0xf bank_mask:0xf
	v_cndmask_b32_dpp v70, v206, v70, vcc quad_perm:[1,0,3,2] row_mask:0xf bank_mask:0xf
	v_cndmask_b32_dpp v71, v207, v71, vcc quad_perm:[1,0,3,2] row_mask:0xf bank_mask:0xf
	global_store_dwordx4 v[80:81], v[208:211], off
	global_store_dwordx4 v[80:81], v[68:71], off offset:1024
	s_mov_b64 vcc, s[100:101]

; __device__ __forceinline__ float gelu_tanh(float x) { const float u = 1.5957691216f * (x + 0.044715f * x * x * x); return x * __builtin_amdgcn_rcpf(1.f + __expf(-u)); }
; __device__ __forceinline__ void st_bf16x8(bf16_t* p, const f32x4 a, const f32x4 b) { uint4 o; o.x = cvt_pk_bf16(a[0], a[1]); o.y = cvt_pk_bf16(a[2], a[3]); o.z = cvt_pk_bf16(b[0], b[1]); o.w = cvt_pk_bf16(b[2], b[3]); *(uint4*)p = o; }
;     __device__ __forceinline__ void row(const f32x4 (&a)[2][2], int row, int pn, int wc, int fq) const {
;         if (pn < 2 || pn == 4 || pn == 5) {
;             bf16_t* dst = (pn < 2 ? pU : pBG) + (size_t)row * 512 + (pn & 1) * 256 + wc * 32 + 8 * fq;
; #pragma unroll
;             for (int bj = 0; bj < 2; ++bj) { f32x4 v0 = a[bj][0], v1 = a[bj][1];
;                 if (pn < 2) {
; #pragma unroll
;                     for (int j = 0; j < 4; ++j) { v0[j] = gelu_tanh(v0[j]); v1[j] = gelu_tanh(v1[j]); } }
;                 st_bf16x8(dst + bj * HALF, v0, v1); }
.LBB0_304:
	s_and_b64 s[0:1], s[80:81], exec
	v_ashrrev_i32_e32 v73, 31, v72
	s_cselect_b32 s1, s31, s49
	s_cselect_b32 s0, s30, s48
	v_lshlrev_b64 v[64:65], 10, v[72:73]
	v_lshl_add_u64 v[64:65], s[0:1], 0, v[64:65]
	s_lshl_b32 s64, s61, 1
	v_lshl_add_u64 v[64:65], v[64:65], 0, s[64:65]
	s_lshl_b32 s64, s91, 2
	v_lshl_add_u64 v[64:65], v[64:65], 0, s[64:65]
	v_lshlrev_b32_e32 v66, 1, v142
	v_mov_b32_e32 v67, v141
	v_lshl_add_u64 v[64:65], v[64:65], 0, v[66:67]
	s_and_b64 vcc, exec, s[4:5]
	v_cvt_pk_bf16_f32 v60, v60, v61
	v_cvt_pk_bf16_f32 v61, v62, v63
	v_cvt_pk_bf16_f32 v62, v56, v57
	v_cvt_pk_bf16_f32 v63, v58, v59
	v_mov_b64_e32 v[204:205], v[60:61]
	v_mov_b64_e32 v[206:207], v[62:63]
	s_cbranch_vccnz .LBB0_306
	v_mov_b32_e32 v190, 0x3d372713
	v_mov_b32_e32 v192, 0xbfcc422a
	v_mov_b32_e32 v194, 0x3fb8aa3b
	v_pk_mul_f32 v[196:197], v[48:49], v[190:191] op_sel_hi:[1,0]
	v_pk_mul_f32 v[198:199], v[50:51], v[190:191] op_sel_hi:[1,0]
	v_pk_mul_f32 v[200:201], v[52:53], v[190:191] op_sel_hi:[1,0]
	v_pk_mul_f32 v[202:203], v[54:55], v[190:191] op_sel_hi:[1,0]
	v_pk_mul_f32 v[196:197], v[48:49], v[196:197]
	v_pk_mul_f32 v[198:199], v[50:51], v[198:199]
	v_pk_mul_f32 v[200:201], v[52:53], v[200:201]
	v_pk_mul_f32 v[202:203], v[54:55], v[202:203]
	v_pk_fma_f32 v[196:197], v[48:49], v[196:197], v[48:49]
	v_pk_fma_f32 v[198:199], v[50:51], v[198:199], v[50:51]
	v_pk_fma_f32 v[200:201], v[52:53], v[200:201], v[52:53]
	v_pk_fma_f32 v[202:203], v[54:55], v[202:203], v[54:55]
	v_pk_mul_f32 v[196:197], v[196:197], v[192:193] op_sel_hi:[1,0]
	v_pk_mul_f32 v[198:199], v[198:199], v[192:193] op_sel_hi:[1,0]
	v_pk_mul_f32 v[200:201], v[200:201], v[192:193] op_sel_hi:[1,0]
	v_pk_mul_f32 v[202:203], v[202:203], v[192:193] op_sel_hi:[1,0]
	v_pk_mul_f32 v[196:197], v[196:197], v[194:195] op_sel_hi:[1,0]
	v_pk_mul_f32 v[198:199], v[198:199], v[194:195] op_sel_hi:[1,0]
	v_pk_mul_f32 v[200:201], v[200:201], v[194:195] op_sel_hi:[1,0]
	v_pk_mul_f32 v[202:203], v[202:203], v[194:195] op_sel_hi:[1,0]
	v_exp_f32_e32 v196, v196
	v_exp_f32_e32 v197, v197
	v_exp_f32_e32 v198, v198
	v_exp_f32_e32 v199, v199
	v_exp_f32_e32 v200, v200
	v_exp_f32_e32 v201, v201
	v_exp_f32_e32 v202, v202
	v_exp_f32_e32 v203, v203
	v_pk_add_f32 v[196:197], v[196:197], 1.0 op_sel_hi:[1,0]
	v_pk_add_f32 v[198:199], v[198:199], 1.0 op_sel_hi:[1,0]
	v_pk_add_f32 v[200:201], v[200:201], 1.0 op_sel_hi:[1,0]
	v_pk_add_f32 v[202:203], v[202:203], 1.0 op_sel_hi:[1,0]
	v_rcp_f32_e32 v196, v196
	v_rcp_f32_e32 v197, v197
	v_rcp_f32_e32 v198, v198
	v_rcp_f32_e32 v199, v199
	v_rcp_f32_e32 v200, v200
	v_rcp_f32_e32 v201, v201
	v_rcp_f32_e32 v202, v202
	v_rcp_f32_e32 v203, v203
	v_pk_mul_f32 v[48:49], v[48:49], v[196:197]
	v_pk_mul_f32 v[50:51], v[50:51], v[198:199]
	v_pk_mul_f32 v[52:53], v[52:53], v[200:201]
	v_pk_mul_f32 v[54:55], v[54:55], v[202:203]
	s_nop 0
	s_nop 0
	s_nop 0
	s_nop 0
.LBB0_306:
	v_cvt_pk_bf16_f32 v52, v52, v53
	v_cvt_pk_bf16_f32 v53, v54, v55
	v_cvt_pk_bf16_f32 v54, v48, v49
	s_nop 0
	v_cvt_pk_bf16_f32 v55, v50, v51
	s_mov_b64 s[100:101], vcc
	v_and_b32_e32 v222, 1, v72
	s_movk_i32 s32, 0xfc40
	v_mad_i64_i32 v[64:65], s[98:99], v222, s32, v[64:65]
	v_cmp_eq_u32_e32 vcc, 0, v222
	s_nop 1
	v_cndmask_b32_dpp v208, v52, v204, vcc quad_perm:[1,0,3,2] row_mask:0xf bank_mask:0xf
	v_cndmask_b32_dpp v209, v53, v205, vcc quad_perm:[1,0,3,2] row_mask:0xf bank_mask:0xf
	v_cndmask_b32_dpp v210, v54, v206, vcc quad_perm:[1,0,3,2] row_mask:0xf bank_mask:0xf
	v_cndmask_b32_dpp v211, v55, v207, vcc quad_perm:[1,0,3,2] row_mask:0xf bank_mask:0xf
	v_cmp_ne_u32_e32 vcc, 0, v222
	s_nop 1
	v_cndmask_b32_dpp v52, v204, v52, vcc quad_perm:[1,0,3,2] row_mask:0xf bank_mask:0xf
	v_cndmask_b32_dpp v53, v205, v53, vcc quad_perm:[1,0,3,2] row_mask:0xf bank_mask:0xf
	v_cndmask_b32_dpp v54, v206, v54, vcc quad_perm:[1,0,3,2] row_mask:0xf bank_mask:0xf
	v_cndmask_b32_dpp v55, v207, v55, vcc quad_perm:[1,0,3,2] row_mask:0xf bank_mask:0xf
	global_store_dwordx4 v[64:65], v[208:211], off
	global_store_dwordx4 v[64:65], v[52:55], off offset:1024
	s_mov_b64 vcc, s[100:101]
	v_add_u32_e32 v56, 0x90, v156
	s_and_b64 vcc, exec, s[8:9]
	s_mov_b64 s[0:1], -1
	s_cbranch_vccnz .LBB0_286

; __device__ __forceinline__ float gelu_tanh(float x) { const float u = 1.5957691216f * (x + 0.044715f * x * x * x); return x * __builtin_amdgcn_rcpf(1.f + __expf(-u)); }
; __device__ __forceinline__ void st_bf16x8(bf16_t* p, const f32x4 a, const f32x4 b) { uint4 o; o.x = cvt_pk_bf16(a[0], a[1]); o.y = cvt_pk_bf16(a[2], a[3]); o.z = cvt_pk_bf16(b[0], b[1]); o.w = cvt_pk_bf16(b[2], b[3]); *(uint4*)p = o; }
;     __device__ __forceinline__ void row(const f32x4 (&a)[2][2], int row, int pn, int wc, int fq) const {
;         if (pn < 2 || pn == 4 || pn == 5) {
;             bf16_t* dst = (pn < 2 ? pU : pBG) + (size_t)row * 512 + (pn & 1) * 256 + wc * 32 + 8 * fq;
; #pragma unroll
;             for (int bj = 0; bj < 2; ++bj) { f32x4 v0 = a[bj][0], v1 = a[bj][1];
;                 if (pn < 2) {
; #pragma unroll
;                     for (int j = 0; j < 4; ++j) { v0[j] = gelu_tanh(v0[j]); v1[j] = gelu_tanh(v1[j]); } }
;                 st_bf16x8(dst + bj * HALF, v0, v1); }
.LBB0_320:
	s_and_b64 s[0:1], s[80:81], exec
	v_ashrrev_i32_e32 v57, 31, v56
	s_cselect_b32 s1, s31, s49
	s_cselect_b32 s0, s30, s48
	v_lshlrev_b64 v[48:49], 10, v[56:57]
	v_lshl_add_u64 v[48:49], s[0:1], 0, v[48:49]
	s_lshl_b32 s64, s61, 1
	v_lshl_add_u64 v[48:49], v[48:49], 0, s[64:65]
	s_lshl_b32 s64, s91, 2
	v_lshl_add_u64 v[48:49], v[48:49], 0, s[64:65]
	v_lshlrev_b32_e32 v50, 1, v142
	v_mov_b32_e32 v51, v141
	v_lshl_add_u64 v[48:49], v[48:49], 0, v[50:51]
	s_and_b64 vcc, exec, s[4:5]
	v_cvt_pk_bf16_f32 v44, v44, v45
	v_cvt_pk_bf16_f32 v45, v46, v47
	v_cvt_pk_bf16_f32 v46, v40, v41
	v_cvt_pk_bf16_f32 v47, v42, v43
	v_mov_b64_e32 v[204:205], v[44:45]
	v_mov_b64_e32 v[206:207], v[46:47]
	s_cbranch_vccnz .LBB0_322
	v_mov_b32_e32 v190, 0x3d372713
	v_mov_b32_e32 v192, 0xbfcc422a
	v_mov_b32_e32 v194, 0x3fb8aa3b
	v_pk_mul_f32 v[196:197], v[32:33], v[190:191] op_sel_hi:[1,0]
	v_pk_mul_f32 v[198:199], v[34:35], v[190:191] op_sel_hi:[1,0]
	v_pk_mul_f32 v[200:201], v[36:37], v[190:191] op_sel_hi:[1,0]
	v_pk_mul_f32 v[202:203], v[38:39], v[190:191] op_sel_hi:[1,0]
	v_pk_mul_f32 v[196:197], v[32:33], v[196:197]
	v_pk_mul_f32 v[198:199], v[34:35], v[198:199]
	v_pk_mul_f32 v[200:201], v[36:37], v[200:201]
	v_pk_mul_f32 v[202:203], v[38:39], v[202:203]
	v_pk_fma_f32 v[196:197], v[32:33], v[196:197], v[32:33]
	v_pk_fma_f32 v[198:199], v[34:35], v[198:199], v[34:35]
	v_pk_fma_f32 v[200:201], v[36:37], v[200:201], v[36:37]
	v_pk_fma_f32 v[202:203], v[38:39], v[202:203], v[38:39]
	v_pk_mul_f32 v[196:197], v[196:197], v[192:193] op_sel_hi:[1,0]
	v_pk_mul_f32 v[198:199], v[198:199], v[192:193] op_sel_hi:[1,0]
	v_pk_mul_f32 v[200:201], v[200:201], v[192:193] op_sel_hi:[1,0]
	v_pk_mul_f32 v[202:203], v[202:203], v[192:193] op_sel_hi:[1,0]
	v_pk_mul_f32 v[196:197], v[196:197], v[194:195] op_sel_hi:[1,0]
	v_pk_mul_f32 v[198:199], v[198:199], v[194:195] op_sel_hi:[1,0]
	v_pk_mul_f32 v[200:201], v[200:201], v[194:195] op_sel_hi:[1,0]
	v_pk_mul_f32 v[202:203], v[202:203], v[194:195] op_sel_hi:[1,0]
	v_exp_f32_e32 v196, v196
	v_exp_f32_e32 v197, v197
	v_exp_f32_e32 v198, v198
	v_exp_f32_e32 v199, v199
	v_exp_f32_e32 v200, v200
	v_exp_f32_e32 v201, v201
	v_exp_f32_e32 v202, v202
	v_exp_f32_e32 v203, v203
	v_pk_add_f32 v[196:197], v[196:197], 1.0 op_sel_hi:[1,0]
	v_pk_add_f32 v[198:199], v[198:199], 1.0 op_sel_hi:[1,0]
	v_pk_add_f32 v[200:201], v[200:201], 1.0 op_sel_hi:[1,0]
	v_pk_add_f32 v[202:203], v[202:203], 1.0 op_sel_hi:[1,0]
	v_rcp_f32_e32 v196, v196
	v_rcp_f32_e32 v197, v197
	v_rcp_f32_e32 v198, v198
	v_rcp_f32_e32 v199, v199
	v_rcp_f32_e32 v200, v200
	v_rcp_f32_e32 v201, v201
	v_rcp_f32_e32 v202, v202
	v_rcp_f32_e32 v203, v203
	v_pk_mul_f32 v[32:33], v[32:33], v[196:197]
	v_pk_mul_f32 v[34:35], v[34:35], v[198:199]
	v_pk_mul_f32 v[36:37], v[36:37], v[200:201]
	v_pk_mul_f32 v[38:39], v[38:39], v[202:203]
	s_nop 0
	s_nop 0
	s_nop 0
	s_nop 0
.LBB0_322:
	v_cvt_pk_bf16_f32 v36, v36, v37
	v_cvt_pk_bf16_f32 v37, v38, v39
	v_cvt_pk_bf16_f32 v38, v32, v33
	s_nop 0
	v_cvt_pk_bf16_f32 v39, v34, v35
	s_mov_b64 s[100:101], vcc
	v_and_b32_e32 v222, 1, v56
	s_movk_i32 s32, 0xfc40
	v_mad_i64_i32 v[48:49], s[98:99], v222, s32, v[48:49]
	v_cmp_eq_u32_e32 vcc, 0, v222
	s_nop 1
	v_cndmask_b32_dpp v208, v36, v204, vcc quad_perm:[1,0,3,2] row_mask:0xf bank_mask:0xf
	v_cndmask_b32_dpp v209, v37, v205, vcc quad_perm:[1,0,3,2] row_mask:0xf bank_mask:0xf
	v_cndmask_b32_dpp v210, v38, v206, vcc quad_perm:[1,0,3,2] row_mask:0xf bank_mask:0xf
	v_cndmask_b32_dpp v211, v39, v207, vcc quad_perm:[1,0,3,2] row_mask:0xf bank_mask:0xf
	v_cmp_ne_u32_e32 vcc, 0, v222
	s_nop 1
	v_cndmask_b32_dpp v36, v204, v36, vcc quad_perm:[1,0,3,2] row_mask:0xf bank_mask:0xf
	v_cndmask_b32_dpp v37, v205, v37, vcc quad_perm:[1,0,3,2] row_mask:0xf bank_mask:0xf
	v_cndmask_b32_dpp v38, v206, v38, vcc quad_perm:[1,0,3,2] row_mask:0xf bank_mask:0xf
	v_cndmask_b32_dpp v39, v207, v39, vcc quad_perm:[1,0,3,2] row_mask:0xf bank_mask:0xf
	global_store_dwordx4 v[48:49], v[208:211], off
	global_store_dwordx4 v[48:49], v[36:39], off offset:1024
	s_mov_b64 vcc, s[100:101]
	v_add_u32_e32 v40, 0xa0, v156
	s_and_b64 vcc, exec, s[8:9]
	s_mov_b64 s[0:1], -1
	s_cbranch_vccnz .LBB0_288

; __device__ __forceinline__ float gelu_tanh(float x) { const float u = 1.5957691216f * (x + 0.044715f * x * x * x); return x * __builtin_amdgcn_rcpf(1.f + __expf(-u)); }
; __device__ __forceinline__ void st_bf16x8(bf16_t* p, const f32x4 a, const f32x4 b) { uint4 o; o.x = cvt_pk_bf16(a[0], a[1]); o.y = cvt_pk_bf16(a[2], a[3]); o.z = cvt_pk_bf16(b[0], b[1]); o.w = cvt_pk_bf16(b[2], b[3]); *(uint4*)p = o; }
;     __device__ __forceinline__ void row(const f32x4 (&a)[2][2], int row, int pn, int wc, int fq) const {
;         if (pn < 2 || pn == 4 || pn == 5) {
;             bf16_t* dst = (pn < 2 ? pU : pBG) + (size_t)row * 512 + (pn & 1) * 256 + wc * 32 + 8 * fq;
; #pragma unroll
;             for (int bj = 0; bj < 2; ++bj) { f32x4 v0 = a[bj][0], v1 = a[bj][1];
;                 if (pn < 2) {
; #pragma unroll
;                     for (int j = 0; j < 4; ++j) { v0[j] = gelu_tanh(v0[j]); v1[j] = gelu_tanh(v1[j]); } }
;                 st_bf16x8(dst + bj * HALF, v0, v1); }
.LBB0_336:
	s_and_b64 s[0:1], s[80:81], exec
	v_ashrrev_i32_e32 v41, 31, v40
	s_cselect_b32 s1, s31, s49
	s_cselect_b32 s0, s30, s48
	v_lshlrev_b64 v[32:33], 10, v[40:41]
	v_lshl_add_u64 v[32:33], s[0:1], 0, v[32:33]
	s_lshl_b32 s64, s61, 1
	v_lshl_add_u64 v[32:33], v[32:33], 0, s[64:65]
	s_lshl_b32 s64, s91, 2
	v_lshl_add_u64 v[32:33], v[32:33], 0, s[64:65]
	v_lshlrev_b32_e32 v34, 1, v142
	v_mov_b32_e32 v35, v141
	v_lshl_add_u64 v[32:33], v[32:33], 0, v[34:35]
	s_and_b64 vcc, exec, s[4:5]
	v_cvt_pk_bf16_f32 v28, v28, v29
	v_cvt_pk_bf16_f32 v29, v30, v31
	v_cvt_pk_bf16_f32 v30, v24, v25
	v_cvt_pk_bf16_f32 v31, v26, v27
	v_mov_b64_e32 v[204:205], v[28:29]
	v_mov_b64_e32 v[206:207], v[30:31]
	s_cbranch_vccnz .LBB0_338
	v_mov_b32_e32 v190, 0x3d372713
	v_mov_b32_e32 v192, 0xbfcc422a
	v_mov_b32_e32 v194, 0x3fb8aa3b
	v_pk_mul_f32 v[196:197], v[16:17], v[190:191] op_sel_hi:[1,0]
	v_pk_mul_f32 v[198:199], v[18:19], v[190:191] op_sel_hi:[1,0]
	v_pk_mul_f32 v[200:201], v[20:21], v[190:191] op_sel_hi:[1,0]
	v_pk_mul_f32 v[202:203], v[22:23], v[190:191] op_sel_hi:[1,0]
	v_pk_mul_f32 v[196:197], v[16:17], v[196:197]
	v_pk_mul_f32 v[198:199], v[18:19], v[198:199]
	v_pk_mul_f32 v[200:201], v[20:21], v[200:201]
	v_pk_mul_f32 v[202:203], v[22:23], v[202:203]
	v_pk_fma_f32 v[196:197], v[16:17], v[196:197], v[16:17]
	v_pk_fma_f32 v[198:199], v[18:19], v[198:199], v[18:19]
	v_pk_fma_f32 v[200:201], v[20:21], v[200:201], v[20:21]
	v_pk_fma_f32 v[202:203], v[22:23], v[202:203], v[22:23]
	v_pk_mul_f32 v[196:197], v[196:197], v[192:193] op_sel_hi:[1,0]
	v_pk_mul_f32 v[198:199], v[198:199], v[192:193] op_sel_hi:[1,0]
	v_pk_mul_f32 v[200:201], v[200:201], v[192:193] op_sel_hi:[1,0]
	v_pk_mul_f32 v[202:203], v[202:203], v[192:193] op_sel_hi:[1,0]
	v_pk_mul_f32 v[196:197], v[196:197], v[194:195] op_sel_hi:[1,0]
	v_pk_mul_f32 v[198:199], v[198:199], v[194:195] op_sel_hi:[1,0]
	v_pk_mul_f32 v[200:201], v[200:201], v[194:195] op_sel_hi:[1,0]
	v_pk_mul_f32 v[202:203], v[202:203], v[194:195] op_sel_hi:[1,0]
	v_exp_f32_e32 v196, v196
	v_exp_f32_e32 v197, v197
	v_exp_f32_e32 v198, v198
	v_exp_f32_e32 v199, v199
	v_exp_f32_e32 v200, v200
	v_exp_f32_e32 v201, v201
	v_exp_f32_e32 v202, v202
	v_exp_f32_e32 v203, v203
	v_pk_add_f32 v[196:197], v[196:197], 1.0 op_sel_hi:[1,0]
	v_pk_add_f32 v[198:199], v[198:199], 1.0 op_sel_hi:[1,0]
	v_pk_add_f32 v[200:201], v[200:201], 1.0 op_sel_hi:[1,0]
	v_pk_add_f32 v[202:203], v[202:203], 1.0 op_sel_hi:[1,0]
	v_rcp_f32_e32 v196, v196
	v_rcp_f32_e32 v197, v197
	v_rcp_f32_e32 v198, v198
	v_rcp_f32_e32 v199, v199
	v_rcp_f32_e32 v200, v200
	v_rcp_f32_e32 v201, v201
	v_rcp_f32_e32 v202, v202
	v_rcp_f32_e32 v203, v203
	v_pk_mul_f32 v[16:17], v[16:17], v[196:197]
	v_pk_mul_f32 v[18:19], v[18:19], v[198:199]
	v_pk_mul_f32 v[20:21], v[20:21], v[200:201]
	v_pk_mul_f32 v[22:23], v[22:23], v[202:203]
	s_nop 0
	s_nop 0
	s_nop 0
	s_nop 0
.LBB0_338:
	v_cvt_pk_bf16_f32 v20, v20, v21
	v_cvt_pk_bf16_f32 v21, v22, v23
	v_cvt_pk_bf16_f32 v22, v16, v17
	s_nop 0
	v_cvt_pk_bf16_f32 v23, v18, v19
	s_mov_b64 s[100:101], vcc
	v_and_b32_e32 v222, 1, v40
	s_movk_i32 s32, 0xfc40
	v_mad_i64_i32 v[32:33], s[98:99], v222, s32, v[32:33]
	v_cmp_eq_u32_e32 vcc, 0, v222
	s_nop 1
	v_cndmask_b32_dpp v208, v20, v204, vcc quad_perm:[1,0,3,2] row_mask:0xf bank_mask:0xf
	v_cndmask_b32_dpp v209, v21, v205, vcc quad_perm:[1,0,3,2] row_mask:0xf bank_mask:0xf
	v_cndmask_b32_dpp v210, v22, v206, vcc quad_perm:[1,0,3,2] row_mask:0xf bank_mask:0xf
	v_cndmask_b32_dpp v211, v23, v207, vcc quad_perm:[1,0,3,2] row_mask:0xf bank_mask:0xf
	v_cmp_ne_u32_e32 vcc, 0, v222
	s_nop 1
	v_cndmask_b32_dpp v20, v204, v20, vcc quad_perm:[1,0,3,2] row_mask:0xf bank_mask:0xf
	v_cndmask_b32_dpp v21, v205, v21, vcc quad_perm:[1,0,3,2] row_mask:0xf bank_mask:0xf
	v_cndmask_b32_dpp v22, v206, v22, vcc quad_perm:[1,0,3,2] row_mask:0xf bank_mask:0xf
	v_cndmask_b32_dpp v23, v207, v23, vcc quad_perm:[1,0,3,2] row_mask:0xf bank_mask:0xf
	global_store_dwordx4 v[32:33], v[208:211], off
	global_store_dwordx4 v[32:33], v[20:23], off offset:1024
	s_mov_b64 vcc, s[100:101]
	v_add_u32_e32 v24, 0xb0, v156
	s_and_b64 vcc, exec, s[8:9]
	s_mov_b64 s[0:1], -1
	s_cbranch_vccnz .LBB0_290

; __device__ __forceinline__ float gelu_tanh(float x) { const float u = 1.5957691216f * (x + 0.044715f * x * x * x); return x * __builtin_amdgcn_rcpf(1.f + __expf(-u)); }
; __device__ __forceinline__ void st_bf16x8(bf16_t* p, const f32x4 a, const f32x4 b) { uint4 o; o.x = cvt_pk_bf16(a[0], a[1]); o.y = cvt_pk_bf16(a[2], a[3]); o.z = cvt_pk_bf16(b[0], b[1]); o.w = cvt_pk_bf16(b[2], b[3]); *(uint4*)p = o; }
;     __device__ __forceinline__ void row(const f32x4 (&a)[2][2], int row, int pn, int wc, int fq) const {
;         if (pn < 2 || pn == 4 || pn == 5) {
;             bf16_t* dst = (pn < 2 ? pU : pBG) + (size_t)row * 512 + (pn & 1) * 256 + wc * 32 + 8 * fq;
; #pragma unroll
;             for (int bj = 0; bj < 2; ++bj) { f32x4 v0 = a[bj][0], v1 = a[bj][1];
;                 if (pn < 2) {
; #pragma unroll
;                     for (int j = 0; j < 4; ++j) { v0[j] = gelu_tanh(v0[j]); v1[j] = gelu_tanh(v1[j]); } }
;                 st_bf16x8(dst + bj * HALF, v0, v1); }
.LBB0_354:
	s_and_b64 s[0:1], s[80:81], exec
	v_ashrrev_i32_e32 v25, 31, v24
	s_cselect_b32 s1, s31, s49
	s_cselect_b32 s0, s30, s48
	v_lshlrev_b64 v[16:17], 10, v[24:25]
	v_lshl_add_u64 v[16:17], s[0:1], 0, v[16:17]
	s_lshl_b32 s64, s61, 1
	v_lshl_add_u64 v[16:17], v[16:17], 0, s[64:65]
	s_lshl_b32 s64, s91, 2
	v_lshl_add_u64 v[16:17], v[16:17], 0, s[64:65]
	v_lshlrev_b32_e32 v140, 1, v142
	v_lshl_add_u64 v[16:17], v[16:17], 0, v[140:141]
	s_and_b64 vcc, exec, s[4:5]
	v_cvt_pk_bf16_f32 v12, v12, v13
	v_cvt_pk_bf16_f32 v13, v14, v15
	v_cvt_pk_bf16_f32 v14, v8, v9
	v_cvt_pk_bf16_f32 v15, v10, v11
	v_mov_b64_e32 v[204:205], v[12:13]
	v_mov_b64_e32 v[206:207], v[14:15]
	s_cbranch_vccnz .LBB0_207
	v_mov_b32_e32 v190, 0x3d372713
	v_mov_b32_e32 v192, 0xbfcc422a
	v_mov_b32_e32 v194, 0x3fb8aa3b
	v_pk_mul_f32 v[196:197], v[0:1], v[190:191] op_sel_hi:[1,0]
	v_pk_mul_f32 v[198:199], v[2:3], v[190:191] op_sel_hi:[1,0]
	v_pk_mul_f32 v[200:201], v[4:5], v[190:191] op_sel_hi:[1,0]
	v_pk_mul_f32 v[202:203], v[6:7], v[190:191] op_sel_hi:[1,0]
	v_pk_mul_f32 v[196:197], v[0:1], v[196:197]
	v_pk_mul_f32 v[198:199], v[2:3], v[198:199]
	v_pk_mul_f32 v[200:201], v[4:5], v[200:201]
	v_pk_mul_f32 v[202:203], v[6:7], v[202:203]
	v_pk_fma_f32 v[196:197], v[0:1], v[196:197], v[0:1]
	v_pk_fma_f32 v[198:199], v[2:3], v[198:199], v[2:3]
	v_pk_fma_f32 v[200:201], v[4:5], v[200:201], v[4:5]
	v_pk_fma_f32 v[202:203], v[6:7], v[202:203], v[6:7]
	v_pk_mul_f32 v[196:197], v[196:197], v[192:193] op_sel_hi:[1,0]
	v_pk_mul_f32 v[198:199], v[198:199], v[192:193] op_sel_hi:[1,0]
	v_pk_mul_f32 v[200:201], v[200:201], v[192:193] op_sel_hi:[1,0]
	v_pk_mul_f32 v[202:203], v[202:203], v[192:193] op_sel_hi:[1,0]
	v_pk_mul_f32 v[196:197], v[196:197], v[194:195] op_sel_hi:[1,0]
	v_pk_mul_f32 v[198:199], v[198:199], v[194:195] op_sel_hi:[1,0]
	v_pk_mul_f32 v[200:201], v[200:201], v[194:195] op_sel_hi:[1,0]
	v_pk_mul_f32 v[202:203], v[202:203], v[194:195] op_sel_hi:[1,0]
	v_exp_f32_e32 v196, v196
	v_exp_f32_e32 v197, v197
	v_exp_f32_e32 v198, v198
	v_exp_f32_e32 v199, v199
	v_exp_f32_e32 v200, v200
	v_exp_f32_e32 v201, v201
	v_exp_f32_e32 v202, v202
	v_exp_f32_e32 v203, v203
	v_pk_add_f32 v[196:197], v[196:197], 1.0 op_sel_hi:[1,0]
	v_pk_add_f32 v[198:199], v[198:199], 1.0 op_sel_hi:[1,0]
	v_pk_add_f32 v[200:201], v[200:201], 1.0 op_sel_hi:[1,0]
	v_pk_add_f32 v[202:203], v[202:203], 1.0 op_sel_hi:[1,0]
	v_rcp_f32_e32 v196, v196
	v_rcp_f32_e32 v197, v197
	v_rcp_f32_e32 v198, v198
	v_rcp_f32_e32 v199, v199
	v_rcp_f32_e32 v200, v200
	v_rcp_f32_e32 v201, v201
	v_rcp_f32_e32 v202, v202
	v_rcp_f32_e32 v203, v203
	v_pk_mul_f32 v[0:1], v[0:1], v[196:197]
	v_pk_mul_f32 v[2:3], v[2:3], v[198:199]
	v_pk_mul_f32 v[4:5], v[4:5], v[200:201]
	v_pk_mul_f32 v[6:7], v[6:7], v[202:203]
	s_branch .LBB0_207

; __device__ __forceinline__ float gelu_tanh(float x) { const float u = 1.5957691216f * (x + 0.044715f * x * x * x); return x * __builtin_amdgcn_rcpf(1.f + __expf(-u)); }
; __device__ __forceinline__ void st_bf16x8(bf16_t* p, const f32x4 a, const f32x4 b) { uint4 o; o.x = cvt_pk_bf16(a[0], a[1]); o.y = cvt_pk_bf16(a[2], a[3]); o.z = cvt_pk_bf16(b[0], b[1]); o.w = cvt_pk_bf16(b[2], b[3]); *(uint4*)p = o; }
;     __device__ __forceinline__ void row(const f32x4 (&a)[2][2], int row, int pn, int wc, int fq) const {
;     ...
;             bf16_t* dst = (pn < 2 ? pU : pBG) + (size_t)row * 512 + (pn & 1) * 256 + wc * 32 + 8 * fq;
; #pragma unroll
;             for (int bj = 0; bj < 2; ++bj) { f32x4 v0 = a[bj][0], v1 = a[bj][1];
;                 if (pn < 2) {
; #pragma unroll
;                     for (int j = 0; j < 4; ++j) { v0[j] = gelu_tanh(v0[j]); v1[j] = gelu_tanh(v1[j]); } }
;                 st_bf16x8(dst + bj * HALF, v0, v1); }
.LBB0_366:
	s_nop 0
	v_cvt_pk_bf16_f32 v2, v20, v21
	v_cvt_pk_bf16_f32 v3, v18, v19
	v_cvt_pk_bf16_f32 v4, v24, v25
	v_cvt_pk_bf16_f32 v5, v22, v23
	global_store_dwordx4 v[0:1], v[2:5], off offset:64

; __device__ __forceinline__ float gelu_tanh(float x) { const float u = 1.5957691216f * (x + 0.044715f * x * x * x); return x * __builtin_amdgcn_rcpf(1.f + __expf(-u)); }
; __device__ __forceinline__ void st_bf16x8(bf16_t* p, const f32x4 a, const f32x4 b) { uint4 o; o.x = cvt_pk_bf16(a[0], a[1]); o.y = cvt_pk_bf16(a[2], a[3]); o.z = cvt_pk_bf16(b[0], b[1]); o.w = cvt_pk_bf16(b[2], b[3]); *(uint4*)p = o; }
;     __device__ __forceinline__ void row(const f32x4 (&a)[2][2], int row, int pn, int wc, int fq) const {
;         if (pn < 2 || pn == 4 || pn == 5) {
;             bf16_t* dst = (pn < 2 ? pU : pBG) + (size_t)row * 512 + (pn & 1) * 256 + wc * 32 + 8 * fq;
; #pragma unroll
;             for (int bj = 0; bj < 2; ++bj) { f32x4 v0 = a[bj][0], v1 = a[bj][1];
;                 if (pn < 2) {
; #pragma unroll
;                     for (int j = 0; j < 4; ++j) { v0[j] = gelu_tanh(v0[j]); v1[j] = gelu_tanh(v1[j]); } }
;                 st_bf16x8(dst + bj * HALF, v0, v1); }
.LBB0_385:
	s_and_b64 s[68:69], s[68:69], exec
	v_mov_b32_e32 v17, v11
	s_cselect_b32 s69, s31, s49
	s_cselect_b32 s68, s30, s48
	v_lshlrev_b64 v[0:1], 10, v[16:17]
	s_and_b32 s10, s10, 0x100
	v_lshl_add_u64 v[0:1], s[68:69], 0, v[0:1]
	s_lshl_b32 s10, s10, 1
	v_lshl_add_u64 v[0:1], v[0:1], 0, s[10:11]
	s_lshl_b32 s10, s79, 2
	v_lshl_add_u64 v[0:1], v[0:1], 0, s[10:11]
	v_lshlrev_b32_e32 v10, 1, v8
	v_lshl_add_u64 v[0:1], v[0:1], 0, v[10:11]
	s_and_b64 vcc, exec, s[0:1]
	v_cvt_pk_bf16_f32 v2, v28, v29
	v_cvt_pk_bf16_f32 v3, v26, v27
	v_cvt_pk_bf16_f32 v4, v32, v33
	v_cvt_pk_bf16_f32 v5, v30, v31
	global_store_dwordx4 v[0:1], v[2:5], off
	s_cbranch_vccnz .LBB0_366
	s_nop 0
	v_mul_f32_e32 v3, 0x3d372713, v24
	v_mul_f32_e32 v3, v24, v3
	v_mul_f32_e32 v4, 0x3d372713, v21
	v_fma_f32 v3, v24, v3, v24
	v_mul_f32_e32 v4, v21, v4
	v_mov_b32_e32 v5, v21
	v_mul_f32_e32 v3, 0xbfcc422a, v3
	v_fmac_f32_e32 v5, v5, v4
	v_mul_f32_e32 v3, 0x3fb8aa3b, v3
	v_mul_f32_e32 v4, 0xbfcc422a, v5
	v_exp_f32_e32 v3, v3
	v_mul_f32_e32 v4, 0x3fb8aa3b, v4
	v_exp_f32_e32 v5, v4
	v_mov_b32_e32 v6, v25
	v_add_f32_e32 v3, 1.0, v3
	v_rcp_f32_e32 v4, v3
	v_add_f32_e32 v3, 1.0, v5
	v_mul_f32_e32 v5, 0x3d372713, v25
	v_mul_f32_e32 v5, v25, v5
	v_fmac_f32_e32 v6, v6, v5
	v_mul_f32_e32 v7, 0x3d372713, v22
	v_mul_f32_e32 v2, 0x3d372713, v20
	v_mul_f32_e32 v5, 0xbfcc422a, v6
	v_mul_f32_e32 v6, 0x3d372713, v18
	v_mul_f32_e32 v7, v22, v7
	v_mul_f32_e32 v10, 0x3d372713, v19
	v_mul_f32_e32 v16, 0x3d372713, v23
	v_mul_f32_e32 v2, v20, v2
	v_mul_f32_e32 v6, v18, v6
	v_fma_f32 v7, v22, v7, v22
	v_mul_f32_e32 v10, v19, v10
	v_mul_f32_e32 v16, v23, v16
	v_fma_f32 v2, v20, v2, v20
	v_fma_f32 v6, v18, v6, v18
	v_mul_f32_e32 v7, 0xbfcc422a, v7
	v_fma_f32 v10, v19, v10, v19
	v_fma_f32 v16, v23, v16, v23
	v_mul_f32_e32 v2, 0xbfcc422a, v2
	v_mul_f32_e32 v6, 0xbfcc422a, v6
	v_mul_f32_e32 v7, 0x3fb8aa3b, v7
	v_mul_f32_e32 v10, 0xbfcc422a, v10
	v_mul_f32_e32 v16, 0xbfcc422a, v16
	v_mul_f32_e32 v2, 0x3fb8aa3b, v2
	v_mul_f32_e32 v5, 0x3fb8aa3b, v5
	v_mul_f32_e32 v6, 0x3fb8aa3b, v6
	v_exp_f32_e32 v7, v7
	v_mul_f32_e32 v10, 0x3fb8aa3b, v10
	v_mul_f32_e32 v16, 0x3fb8aa3b, v16
	v_exp_f32_e32 v2, v2
	v_exp_f32_e32 v5, v5
	v_exp_f32_e32 v6, v6
	v_exp_f32_e32 v10, v10
	v_exp_f32_e32 v17, v16
	v_add_f32_e32 v7, 1.0, v7
	v_add_f32_e32 v2, 1.0, v2
	v_add_f32_e32 v5, 1.0, v5
	v_add_f32_e32 v6, 1.0, v6
	v_rcp_f32_e32 v16, v7
	v_add_f32_e32 v7, 1.0, v10
	v_add_f32_e32 v10, 1.0, v17
	v_rcp_f32_e32 v2, v2
	v_rcp_f32_e32 v3, v3
	v_rcp_f32_e32 v6, v6
	v_rcp_f32_e32 v7, v7
	v_rcp_f32_e32 v17, v10
	v_rcp_f32_e32 v5, v5
	v_pk_mul_f32 v[20:21], v[20:21], v[2:3]
	v_pk_mul_f32 v[18:19], v[18:19], v[6:7]
	v_pk_mul_f32 v[22:23], v[22:23], v[16:17]
	v_pk_mul_f32 v[24:25], v[24:25], v[4:5]
	s_branch .LBB0_366
